# v23 + wait-to-first-consumer (7.2): leading half waits only vmcnt(8) before its barrier, the LDS wait for the V fragments moves behind it
# baseline (speedup 1.0000x reference)
.LqL_g0:
	v_exp_f32_e32 v64, v64
	v_exp_f32_e32 v65, v65
	v_exp_f32_e32 v66, v66
	v_exp_f32_e32 v67, v67
	v_add_f32_e32 v184, v64, v65
	v_exp_f32_e32 v68, v68
	v_exp_f32_e32 v69, v69
	v_cvt_pk_bf16_f32 v64, v64, v65
	v_add_f32_e32 v185, v66, v67
	v_cvt_pk_bf16_f32 v65, v66, v67
	v_exp_f32_e32 v70, v70
	v_exp_f32_e32 v71, v71
	v_add_f32_e32 v186, v68, v69
	v_cvt_pk_bf16_f32 v66, v68, v69
	v_add_f32_e32 v184, v184, v185
	v_add_f32_e32 v187, v70, v71
	v_cvt_pk_bf16_f32 v67, v70, v71
	v_add_f32_e32 v186, v186, v187
	v_add_f32_e32 v184, v184, v186
	v_add_f32_e32 v206, v206, v184
	s_waitcnt vmcnt(8)
	s_barrier
	s_waitcnt lgkmcnt(0)
	s_add_i32 s54, s33, 1
	s_setprio 1
	s_cmp_eq_u32 s54, 1
	s_cbranch_scc1 .LqL_full
	s_cmp_eq_u32 s54, 29
	s_cbranch_scc1 .LqL_full
	s_add_u32 s70, s70, 0x2000
	s_addc_u32 s71, s71, 0
	s_add_u32 s66, s66, 0x80
	s_addc_u32 s67, s67, 0

.LqL_full:
	s_cmp_lt_u32 s54, 29
	s_cselect_b32 s67, s13, s53
	s_cselect_b32 s55, 3, 0xffffffe3
	s_cselect_b32 s66, s22, s12
	s_or_b32 s70, s67, 8
	s_add_i32 s33, s55, s33
	s_ashr_i32 s71, s70, 31
	s_add_i32 s68, s33, 1
	s_lshl_b64 s[70:71], s[70:71], 18
	s_add_u32 s33, s8, s70
	s_addc_u32 s55, s9, s71
	s_ashr_i32 s69, s68, 31
	s_lshl_b64 s[70:71], s[68:69], 13
	s_add_u32 s70, s33, s70
	s_addc_u32 s71, s55, s71
	s_ashr_i32 s67, s66, 31
	s_lshl_b64 s[66:67], s[66:67], 12
	s_add_u32 s33, s10, s66
	s_addc_u32 s55, s11, s67
	s_lshl_b32 s66, s68, 6
	s_ashr_i32 s67, s66, 31
	s_lshl_b64 s[66:67], s[66:67], 1
	s_add_u32 s66, s33, s66
	s_addc_u32 s67, s55, s67
	s_branch .LqL_ldsb
	s_nop 0
	s_nop 0
	s_nop 0
	s_nop 0
	s_nop 0
	s_nop 0
	s_nop 0
	s_nop 0
	s_nop 0
	s_nop 0
	s_nop 0
	s_nop 0
	s_nop 0
	s_nop 0
	s_nop 0
